# attention tile loop: one static s_setprio 1 for the younger wave half (strategy 4 / asm guide 7.4)
# baseline (speedup 1.0000x reference)
.LBB0_365:
	v_readlane_b32 s0, v255, 23
	s_sub_i32 s6, s0, s8
	s_cmpk_gt_i32 s8, 0x87
	s_cselect_b64 s[0:1], -1, 0
	s_and_b64 s[12:13], s[0:1], exec
	s_cselect_b32 s30, s6, s7
	s_cmp_lt_i32 s30, 0
	s_mov_b64 s[6:7], -1
	s_cbranch_scc0 .LBB0_404
	s_and_b64 s[0:1], s[0:1], exec
	s_cselect_b32 s0, 0xffff, s8
	s_sext_i32_i16 s1, s0
	s_mulk_i32 s1, 0x7879
	s_lshr_b32 s6, s1, 31
	s_ashr_i32 s1, s1, 19
	s_add_i32 s6, s1, s6
	s_mul_i32 s1, s6, 17
	s_sub_i32 s12, s0, s1
	s_sub_i32 s0, 16, s12
	s_and_b32 s13, s0, 0xffff
	s_mov_b64 s[40:41], s[54:55]
	s_mov_b64 s[8:9], s[54:55]
	s_mov_b64 s[0:1], s[4:5]
	s_lshl_b32 s7, s6, 3
	v_mov_b32_e32 v177, v148
	global_load_dwordx2 v[160:161], v1, s[0:1] offset:72
	s_ashr_i32 s31, s6, 1
	s_and_b32 s0, s7, 8
	v_readlane_b32 s1, v254, 52
	s_or_b32 s14, s0, s1
	v_readfirstlane_b32 s61, v177
	s_ashr_i32 s65, s61, 8
	s_bfe_u32 s64, s61, 0x20006
	s_mul_i32 s6, s31, 0x4488000
	s_mul_hi_i32 s7, s31, 0x4488000
	s_add_u32 s0, s40, s6
	s_addc_u32 s1, s41, s7
	s_add_u32 s0, s0, 0x198a0200
	s_addc_u32 s1, s1, 0
	s_lshl_b32 s68, s13, 7
	s_lshl_b32 s69, s64, 5
	v_and_b32_e32 v182, 31, v177
	s_or_b32 s22, s69, s68
	v_or_b32_e32 v158, s22, v182
	v_mul_u32_u24_e32 v0, 0x4080, v158
	v_mov_b64_e32 v[2:3], s[0:1]
	v_lshl_add_u64 v[4:5], v[0:1], 1, s[0:1]
	s_lshl_b32 s60, s14, 7
	s_lshl_b32 s14, s14, 8
	s_lshl_b32 s0, s65, 6
	v_lshl_add_u64 v[4:5], v[4:5], 0, s[14:15]
	s_ashr_i32 s1, s0, 31
	v_bfe_u32 v22, v177, 5, 1
	v_lshl_add_u64 v[4:5], s[0:1], 1, v[4:5]
	s_and_b32 s0, s12, 0xffff
	s_lshl_b32 s66, s13, 1
	v_lshlrev_b32_e32 v0, 4, v22
	s_cmp_lg_u32 s0, 16
	v_lshl_add_u64 v[4:5], v[4:5], 0, v[0:1]
	s_cselect_b64 s[0:1], -1, 0
	v_ashrrev_i32_e32 v183, 4, v177
	global_load_dwordx4 v[112:115], v[4:5], off
	global_load_dwordx4 v[116:119], v[4:5], off offset:32
	global_load_dwordx4 v[120:123], v[4:5], off offset:64
	global_load_dwordx4 v[124:127], v[4:5], off offset:96
	v_mad_i64_i32 v[14:15], s[12:13], v183, s47, 0
	v_mad_i64_i32 v[2:3], s[12:13], v183, s47, v[2:3]
	v_lshlrev_b32_e32 v4, 4, v177
	s_and_b64 s[12:13], s[0:1], exec
	v_lshl_add_u64 v[2:3], v[2:3], 0, s[14:15]
	v_and_b32_e32 v20, 0xf0, v4
	v_mov_b32_e32 v21, v1
	s_cselect_b32 s12, 64, 0
	v_lshl_add_u64 v[2:3], v[2:3], 0, v[20:21]
	s_mul_i32 s14, s12, 0x8100
	v_lshl_add_u64 v[2:3], v[2:3], 0, s[14:15]
	s_movk_i32 s13, 0x2000
	v_add_co_u32_e32 v4, vcc, s13, v2
	s_mov_b32 s13, 0x104000
	s_nop 0
	v_addc_co_u32_e32 v5, vcc, 0, v3, vcc
	v_add_co_u32_e32 v2, vcc, s13, v2
	global_load_dwordx4 v[10:13], v[4:5], off offset:-4096
	global_load_dwordx4 v[16:19], v[4:5], off
	v_addc_co_u32_e32 v3, vcc, 0, v3, vcc
	global_load_dwordx4 v[6:9], v[2:3], off offset:-4096
	s_nop 0
	global_load_dwordx4 v[2:5], v[2:3], off
	v_cndmask_b32_e64 v21, 0, 1, s[0:1]
	v_add_u32_e32 v23, s12, v183
	s_movk_i32 s0, 0x70
	v_cmp_gt_i32_e32 vcc, s0, v23
	s_movk_i32 s0, 0x110
	v_mul_lo_u32 v180, v183, s0
	s_movk_i32 s0, 0x140
	v_mul_lo_u32 v181, v183, s0
	s_movk_i32 s0, 0x50
	v_lshlrev_b32_e32 v178, 2, v22
	s_add_i32 s14, s66, 2
	s_cmpk_lt_u32 s61, 0x100
	v_add_u32_e32 v179, 0, v20
	s_cselect_b64 s[26:27], -1, 0
	s_mov_b32 s22, 0x204000
	v_readfirstlane_b32 s67, v21
	s_mov_b64 s[12:13], -1
	v_cmp_lt_i32_e64 s[38:39], 15, v183
	v_mul_lo_u32 v164, v21, s22
	s_waitcnt vmcnt(3)
	v_cndmask_b32_e64 v131, v13, 0, vcc
	v_cndmask_b32_e64 v130, v12, 0, vcc
	v_cndmask_b32_e64 v129, v11, 0, vcc
	v_cndmask_b32_e64 v128, v10, 0, vcc
	s_waitcnt vmcnt(2)
	v_cndmask_b32_e64 v135, v19, 0, vcc
	v_cndmask_b32_e64 v134, v18, 0, vcc
	v_cndmask_b32_e64 v133, v17, 0, vcc
	v_cndmask_b32_e64 v132, v16, 0, vcc
	v_cmp_gt_i32_e32 vcc, s0, v23
	v_add_u32_e32 v10, v179, v180
	v_add_u32_e32 v11, v179, v181
	s_waitcnt vmcnt(0)
	v_cndmask_b32_e64 v140, v2, 0, vcc
	v_lshrrev_b32_e32 v2, 2, v177
	v_cndmask_b32_e64 v142, v4, 0, vcc
	v_cndmask_b32_e64 v141, v3, 0, vcc
	v_and_or_b32 v2, v2, 3, v178
	v_and_b32_e32 v3, 16, v177
	v_lshlrev_b32_e32 v4, 2, v177
	v_mul_u32_u24_e32 v2, 0x140, v2
	v_and_or_b32 v3, v4, 12, v3
	v_lshl_or_b32 v184, v3, 1, v2
	v_sub_u32_e32 v2, v178, v182
	v_and_b32_e32 v3, 15, v177
	v_cndmask_b32_e64 v139, v9, 0, vcc
	v_cndmask_b32_e64 v138, v8, 0, vcc
	v_cndmask_b32_e64 v137, v7, 0, vcc
	v_cndmask_b32_e64 v136, v6, 0, vcc
	v_cndmask_b32_e64 v143, v5, 0, vcc
	s_and_b64 vcc, exec, s[26:27]
	v_cmp_lt_i32_e64 s[0:1], 47, v183
	v_subrev_u32_e32 v185, s69, v2
	v_lshlrev_b32_e32 v162, 4, v3
	ds_write_b128 v10, v[128:131]
	ds_write_b128 v11, v[132:135] offset:34816
	ds_write_b128 v10, v[136:139] offset:8704
	ds_write_b128 v11, v[140:143] offset:45056
	s_waitcnt lgkmcnt(0)
	s_barrier
	s_cbranch_vccnz .LBB0_384
	s_setprio 1
	s_cmp_lg_u32 0, -1
	s_cselect_b32 s12, 0, 0
	s_add_i32 s12, s12, 0x8800
	v_add_u32_e32 v186, s12, v184
	s_movk_i32 s12, 0x110
	v_mad_u32_u24 v2, v182, s12, 0
	s_lshl_b32 s12, s65, 7
	v_add3_u32 v187, v2, v0, s12
	s_lshl_b32 s78, s67, 6
	v_subrev_u32_e32 v2, s68, v185
	v_add_u32_e32 v2, s78, v2
	s_add_i32 s12, s68, s69
	v_add_u32_e32 v189, 59, v2
	v_add_u32_e32 v190, 32, v2
	v_add_u32_e32 v191, 11, v2
	v_add_u32_e32 v192, 10, v2
	v_add_u32_e32 v193, 9, v2
	v_add_u32_e32 v194, 8, v2
	v_add_u32_e32 v195, 3, v2
	v_add_u32_e32 v196, 2, v2
	v_add_u32_e32 v197, 1, v2
	v_add_u32_e32 v2, s12, v182
	v_sub_u32_e32 v2, v2, v178
	v_mov_b32_e32 v165, v1
	v_subrev_u32_e32 v198, s78, v2
	v_lshl_add_u64 v[2:3], s[6:7], 0, v[164:165]
	s_lshl_b32 s12, s60, 1
	v_lshl_add_u64 v[2:3], v[2:3], 0, v[14:15]
	v_mov_b32_e32 v163, v1
	s_add_u32 s12, s40, s12
	v_lshl_add_u64 v[2:3], v[2:3], 0, v[162:163]
	s_addc_u32 s13, s41, 0
	v_lshl_add_u64 v[2:3], s[12:13], 0, v[2:3]
	s_mov_b64 s[12:13], 0x19ba8200
	v_mov_b32_e32 v30, v1
	v_mov_b32_e32 v31, v1
	v_lshl_add_u64 v[166:167], v[2:3], 0, s[12:13]
	v_mov_b32_e32 v16, v1
	v_mov_b32_e32 v17, v1
	v_mov_b32_e32 v18, v1
	v_mov_b32_e32 v19, v1
	v_mov_b32_e32 v20, v1
	v_mov_b32_e32 v21, v1
	v_mov_b32_e32 v22, v1
	v_mov_b32_e32 v23, v1
	v_mov_b32_e32 v24, v1
	v_mov_b32_e32 v25, v1
	v_mov_b32_e32 v26, v1
	v_mov_b32_e32 v27, v1
	v_mov_b32_e32 v28, v1
	v_mov_b32_e32 v29, v1
	v_mov_b64_e32 v[46:47], v[30:31]
	v_mov_b64_e32 v[62:63], v[30:31]
	v_mov_b64_e32 v[78:79], v[30:31]
	v_mov_b64_e32 v[6:7], v[136:137]
	v_mov_b64_e32 v[2:3], v[128:129]
	v_mov_b64_e32 v[146:147], v[142:143]
	v_mov_b64_e32 v[10:11], v[132:133]
	s_mov_b32 s77, 0
	v_mov_b32_e32 v149, v158
	v_or_b32_e32 v188, s78, v178
	s_mov_b32 s23, 2
	v_mov_b32_e32 v163, 0
	v_mov_b32_e32 v165, 0xff800000
	v_mov_b64_e32 v[44:45], v[28:29]
	v_mov_b64_e32 v[42:43], v[26:27]
	v_mov_b64_e32 v[40:41], v[24:25]
	v_mov_b64_e32 v[38:39], v[22:23]
	v_mov_b64_e32 v[36:37], v[20:21]
	v_mov_b64_e32 v[34:35], v[18:19]
	v_mov_b64_e32 v[32:33], v[16:17]
	v_mov_b64_e32 v[60:61], v[28:29]
	v_mov_b64_e32 v[58:59], v[26:27]
	v_mov_b64_e32 v[56:57], v[24:25]
	v_mov_b64_e32 v[54:55], v[22:23]
	v_mov_b64_e32 v[52:53], v[20:21]
	v_mov_b64_e32 v[50:51], v[18:19]
	v_mov_b64_e32 v[48:49], v[16:17]
	v_mov_b64_e32 v[76:77], v[28:29]
	v_mov_b64_e32 v[74:75], v[26:27]
	v_mov_b64_e32 v[72:73], v[24:25]
	v_mov_b64_e32 v[70:71], v[22:23]
	v_mov_b64_e32 v[68:69], v[20:21]
	v_mov_b64_e32 v[66:67], v[18:19]
	v_mov_b64_e32 v[64:65], v[16:17]
	v_mov_b64_e32 v[8:9], v[138:139]
	v_mov_b64_e32 v[4:5], v[130:131]
	v_mov_b64_e32 v[144:145], v[140:141]
	v_mov_b64_e32 v[12:13], v[134:135]
	s_mov_b32 s79, 0
	s_mov_b32 s42, 0
	s_mov_b32 s22, s67

.LBB0_403:
	s_setprio 0
	s_mov_b64 s[6:7], 0
	s_barrier
